# hand-written prologue weight-transpose loop: 8 loads in flight per item, scalar Seg metadata
# speedup vs baseline: 1.0119x; 1.0119x over previous
.LBB0_371:
	s_or_b64 exec, exec, s[4:5]
	v_lshrrev_b32_e32 v0, 6, v198
	v_and_b32_e32 v1, 63, v198
	v_and_b32_e32 v2, 7, v198
	v_readfirstlane_b32 s4, v0
	v_bfe_u32 v3, v198, 3, 3
	s_lshl_b32 s5, s2, 3
	s_add_u32 s32, s5, s4
	s_mul_i32 s5, s4, 0x2100
	s_cmp_ge_u32 s32, s57
	s_cbranch_scc1 .Lw_done
	v_mul_u32_u24_e32 v4, 0x84, v3
	v_lshl_add_u32 v4, v2, 4, v4
	v_add_u32_e32 v4, s5, v4
	v_mul_u32_u24_e32 v5, 0x420, v2
	v_lshl_add_u32 v5, v3, 2, v5
	v_add_u32_e32 v5, s5, v5
	v_mul_u32_u24_e32 v6, 56, v1
	v_mov_b32_e32 v7, 0x7fffffff
	v_lshlrev_b32_e32 v76, 4, v2
	v_cmp_ge_u32_e32 vcc, s17, v1
	s_and_saveexec_b64 s[8:9], vcc
	global_load_dword v7, v6, s[94:95] offset:232
	s_mov_b64 exec, s[8:9]
	s_waitcnt vmcnt(0)
.Lw_item:
	v_cmp_ge_u32_e32 vcc, s32, v7
	s_nop 3
	s_bcnt1_i32_b64 s38, vcc
	s_add_i32 s38, s38, -1
	s_mul_i32 s38, s38, 56
	s_add_u32 s38, s94, s38
	s_addc_u32 s39, s95, 0
	s_load_dwordx2 s[4:5], s[38:39], 0xb8
	s_load_dwordx2 s[6:7], s[38:39], 0xc0
	s_load_dwordx2 s[40:41], s[38:39], 0xc8
	s_load_dwordx2 s[42:43], s[38:39], 0xd0
	s_load_dwordx2 s[8:9], s[38:39], 0xd8
	s_load_dwordx2 s[12:13], s[38:39], 0xe0
	s_load_dwordx2 s[18:19], s[38:39], 0xe8
	s_waitcnt lgkmcnt(0)
	s_sub_u32 s38, s32, s18
	s_add_i32 s39, s8, 31
	s_lshr_b32 s39, s39, 5
	v_cvt_f32_u32_e32 v8, s38
	v_cvt_f32_u32_e32 v9, s39
	v_add_f32_e32 v8, 0.5, v8
	v_rcp_f32_e32 v9, v9
	s_nop 0
	v_mul_f32_e32 v8, v8, v9
	v_cvt_u32_f32_e32 v8, v8
	s_nop 0
	v_readfirstlane_b32 s28, v8
	s_nop 3
	s_mul_i32 s29, s28, s39
	s_sub_u32 s29, s38, s29
	s_lshl_b32 s28, s28, 6
	s_lshl_b32 s29, s29, 5
	v_add_u32_e32 v8, s28, v3
	v_mul_lo_u32 v9, v8, s42
	s_add_i32 s38, s43, s29
	v_lshl_add_u32 v10, v2, 2, s38
	v_add_lshl_u32 v56, v9, v10, 2
	s_lshl_b32 s38, s42, 5
	v_add_u32_e32 v57, s38, v56
	v_add_u32_e32 v58, s38, v57
	v_add_u32_e32 v59, s38, v58
	v_add_u32_e32 v60, s38, v59
	v_add_u32_e32 v61, s38, v60
	v_add_u32_e32 v62, s38, v61
	v_add_u32_e32 v63, s38, v62
	s_cmp_eq_u64 s[4:5], 0
	s_cbranch_scc1 .Lw_nosrc
	global_load_dwordx4 v[16:19], v56, s[4:5]
	global_load_dwordx4 v[20:23], v57, s[4:5]
	global_load_dwordx4 v[24:27], v58, s[4:5]
	global_load_dwordx4 v[28:31], v59, s[4:5]
	global_load_dwordx4 v[32:35], v60, s[4:5]
	global_load_dwordx4 v[36:39], v61, s[4:5]
	global_load_dwordx4 v[40:43], v62, s[4:5]
	global_load_dwordx4 v[44:47], v63, s[4:5]
	s_branch .Lw_src_done
.Lw_nosrc:
	v_mov_b32_e32 v16, 0
	v_mov_b32_e32 v17, 0
	v_mov_b32_e32 v18, 0
	v_mov_b32_e32 v19, 0
	v_mov_b32_e32 v20, 0
	v_mov_b32_e32 v21, 0
	v_mov_b32_e32 v22, 0
	v_mov_b32_e32 v23, 0
	v_mov_b32_e32 v24, 0
	v_mov_b32_e32 v25, 0
	v_mov_b32_e32 v26, 0
	v_mov_b32_e32 v27, 0
	v_mov_b32_e32 v28, 0
	v_mov_b32_e32 v29, 0
	v_mov_b32_e32 v30, 0
	v_mov_b32_e32 v31, 0
	v_mov_b32_e32 v32, 0
	v_mov_b32_e32 v33, 0
	v_mov_b32_e32 v34, 0
	v_mov_b32_e32 v35, 0
	v_mov_b32_e32 v36, 0
	v_mov_b32_e32 v37, 0
	v_mov_b32_e32 v38, 0
	v_mov_b32_e32 v39, 0
	v_mov_b32_e32 v40, 0
	v_mov_b32_e32 v41, 0
	v_mov_b32_e32 v42, 0
	v_mov_b32_e32 v43, 0
	v_mov_b32_e32 v44, 0
	v_mov_b32_e32 v45, 0
	v_mov_b32_e32 v46, 0
	v_mov_b32_e32 v47, 0
.Lw_src_done:
	v_mov_b32_e32 v48, s19
	v_mov_b32_e32 v49, s19
	v_mov_b32_e32 v50, s19
	v_mov_b32_e32 v51, s19
	v_mov_b32_e32 v52, s19
	v_mov_b32_e32 v53, s19
	v_mov_b32_e32 v54, s19
	v_mov_b32_e32 v55, s19
	s_cmp_eq_u64 s[6:7], 0
	s_cbranch_scc1 .Lw_noscale
	v_lshlrev_b32_e32 v9, 2, v8
	global_load_dword v64, v9, s[6:7]
	global_load_dword v65, v9, s[6:7] offset:32
	global_load_dword v66, v9, s[6:7] offset:64
	global_load_dword v67, v9, s[6:7] offset:96
	global_load_dword v68, v9, s[6:7] offset:128
	global_load_dword v69, v9, s[6:7] offset:160
	global_load_dword v70, v9, s[6:7] offset:192
	global_load_dword v71, v9, s[6:7] offset:224
	s_waitcnt vmcnt(0)
	v_mul_f32_e32 v48, v48, v64
	v_mul_f32_e32 v49, v49, v65
	v_mul_f32_e32 v50, v50, v66
	v_mul_f32_e32 v51, v51, v67
	v_mul_f32_e32 v52, v52, v68
	v_mul_f32_e32 v53, v53, v69
	v_mul_f32_e32 v54, v54, v70
	v_mul_f32_e32 v55, v55, v71
.Lw_noscale:
	s_waitcnt vmcnt(0)
	v_mul_f32_e32 v16, v16, v48
	v_mul_f32_e32 v17, v17, v48
	v_mul_f32_e32 v18, v18, v48
	v_mul_f32_e32 v19, v19, v48
	v_mul_f32_e32 v20, v20, v49
	v_mul_f32_e32 v21, v21, v49
	v_mul_f32_e32 v22, v22, v49
	v_mul_f32_e32 v23, v23, v49
	v_mul_f32_e32 v24, v24, v50
	v_mul_f32_e32 v25, v25, v50
	v_mul_f32_e32 v26, v26, v50
	v_mul_f32_e32 v27, v27, v50
	v_mul_f32_e32 v28, v28, v51
	v_mul_f32_e32 v29, v29, v51
	v_mul_f32_e32 v30, v30, v51
	v_mul_f32_e32 v31, v31, v51
	v_mul_f32_e32 v32, v32, v52
	v_mul_f32_e32 v33, v33, v52
	v_mul_f32_e32 v34, v34, v52
	v_mul_f32_e32 v35, v35, v52
	v_mul_f32_e32 v36, v36, v53
	v_mul_f32_e32 v37, v37, v53
	v_mul_f32_e32 v38, v38, v53
	v_mul_f32_e32 v39, v39, v53
	v_mul_f32_e32 v40, v40, v54
	v_mul_f32_e32 v41, v41, v54
	v_mul_f32_e32 v42, v42, v54
	v_mul_f32_e32 v43, v43, v54
	v_mul_f32_e32 v44, v44, v55
	v_mul_f32_e32 v45, v45, v55
	v_mul_f32_e32 v46, v46, v55
	v_mul_f32_e32 v47, v47, v55
	ds_write_b32 v4, v16
	ds_write_b32 v4, v17 offset:4
	ds_write_b32 v4, v18 offset:8
	ds_write_b32 v4, v19 offset:12
	ds_write_b32 v4, v20 offset:1056
	ds_write_b32 v4, v21 offset:1060
	ds_write_b32 v4, v22 offset:1064
	ds_write_b32 v4, v23 offset:1068
	ds_write_b32 v4, v24 offset:2112
	ds_write_b32 v4, v25 offset:2116
	ds_write_b32 v4, v26 offset:2120
	ds_write_b32 v4, v27 offset:2124
	ds_write_b32 v4, v28 offset:3168
	ds_write_b32 v4, v29 offset:3172
	ds_write_b32 v4, v30 offset:3176
	ds_write_b32 v4, v31 offset:3180
	ds_write_b32 v4, v32 offset:4224
	ds_write_b32 v4, v33 offset:4228
	ds_write_b32 v4, v34 offset:4232
	ds_write_b32 v4, v35 offset:4236
	ds_write_b32 v4, v36 offset:5280
	ds_write_b32 v4, v37 offset:5284
	ds_write_b32 v4, v38 offset:5288
	ds_write_b32 v4, v39 offset:5292
	ds_write_b32 v4, v40 offset:6336
	ds_write_b32 v4, v41 offset:6340
	ds_write_b32 v4, v42 offset:6344
	ds_write_b32 v4, v43 offset:6348
	ds_write_b32 v4, v44 offset:7392
	ds_write_b32 v4, v45 offset:7396
	ds_write_b32 v4, v46 offset:7400
	ds_write_b32 v4, v47 offset:7404
	s_waitcnt lgkmcnt(0)
	s_cmp_lg_u32 s13, 0
	s_cselect_b64 s[38:39], -1, 0
	ds_read_b32 v64, v5
	ds_read_b32 v65, v5 offset:132
	ds_read_b32 v66, v5 offset:264
	ds_read_b32 v67, v5 offset:396
	ds_read_b32 v68, v5 offset:528
	ds_read_b32 v69, v5 offset:660
	ds_read_b32 v70, v5 offset:792
	ds_read_b32 v71, v5 offset:924
	s_add_i32 s4, s29, 0
	v_add_u32_e32 v8, s4, v3
	v_lshrrev_b32_e32 v9, 7, v8
	v_and_b32_e32 v10, 0x7f, v8
	v_lshl_add_u32 v9, v9, 8, v10
	v_cndmask_b32_e64 v8, v8, v9, s[38:39]
	v_add_u32_e32 v8, s12, v8
	v_mul_lo_u32 v8, v8, s9
	v_add_u32_e32 v8, s28, v8
	v_lshl_add_u32 v8, v8, 1, v76
	s_waitcnt lgkmcnt(0)
	v_cvt_pk_bf16_f32 v72, v64, v65
	v_cvt_pk_bf16_f32 v73, v66, v67
	v_cvt_pk_bf16_f32 v74, v68, v69
	v_cvt_pk_bf16_f32 v75, v70, v71
	global_store_dwordx4 v8, v[72:75], s[40:41]
	ds_read_b32 v64, v5 offset:32
	ds_read_b32 v65, v5 offset:164
	ds_read_b32 v66, v5 offset:296
	ds_read_b32 v67, v5 offset:428
	ds_read_b32 v68, v5 offset:560
	ds_read_b32 v69, v5 offset:692
	ds_read_b32 v70, v5 offset:824
	ds_read_b32 v71, v5 offset:956
	s_add_i32 s4, s29, 8
	v_add_u32_e32 v8, s4, v3
	v_lshrrev_b32_e32 v9, 7, v8
	v_and_b32_e32 v10, 0x7f, v8
	v_lshl_add_u32 v9, v9, 8, v10
	v_cndmask_b32_e64 v8, v8, v9, s[38:39]
	v_add_u32_e32 v8, s12, v8
	v_mul_lo_u32 v8, v8, s9
	v_add_u32_e32 v8, s28, v8
	v_lshl_add_u32 v8, v8, 1, v76
	s_waitcnt lgkmcnt(0)
	v_cvt_pk_bf16_f32 v72, v64, v65
	v_cvt_pk_bf16_f32 v73, v66, v67
	v_cvt_pk_bf16_f32 v74, v68, v69
	v_cvt_pk_bf16_f32 v75, v70, v71
	global_store_dwordx4 v8, v[72:75], s[40:41]
	ds_read_b32 v64, v5 offset:64
	ds_read_b32 v65, v5 offset:196
	ds_read_b32 v66, v5 offset:328
	ds_read_b32 v67, v5 offset:460
	ds_read_b32 v68, v5 offset:592
	ds_read_b32 v69, v5 offset:724
	ds_read_b32 v70, v5 offset:856
	ds_read_b32 v71, v5 offset:988
	s_add_i32 s4, s29, 16
	v_add_u32_e32 v8, s4, v3
	v_lshrrev_b32_e32 v9, 7, v8
	v_and_b32_e32 v10, 0x7f, v8
	v_lshl_add_u32 v9, v9, 8, v10
	v_cndmask_b32_e64 v8, v8, v9, s[38:39]
	v_add_u32_e32 v8, s12, v8
	v_mul_lo_u32 v8, v8, s9
	v_add_u32_e32 v8, s28, v8
	v_lshl_add_u32 v8, v8, 1, v76
	s_waitcnt lgkmcnt(0)
	v_cvt_pk_bf16_f32 v72, v64, v65
	v_cvt_pk_bf16_f32 v73, v66, v67
	v_cvt_pk_bf16_f32 v74, v68, v69
	v_cvt_pk_bf16_f32 v75, v70, v71
	global_store_dwordx4 v8, v[72:75], s[40:41]
	ds_read_b32 v64, v5 offset:96
	ds_read_b32 v65, v5 offset:228
	ds_read_b32 v66, v5 offset:360
	ds_read_b32 v67, v5 offset:492
	ds_read_b32 v68, v5 offset:624
	ds_read_b32 v69, v5 offset:756
	ds_read_b32 v70, v5 offset:888
	ds_read_b32 v71, v5 offset:1020
	s_add_i32 s4, s29, 24
	v_add_u32_e32 v8, s4, v3
	v_lshrrev_b32_e32 v9, 7, v8
	v_and_b32_e32 v10, 0x7f, v8
	v_lshl_add_u32 v9, v9, 8, v10
	v_cndmask_b32_e64 v8, v8, v9, s[38:39]
	v_add_u32_e32 v8, s12, v8
	v_mul_lo_u32 v8, v8, s9
	v_add_u32_e32 v8, s28, v8
	v_lshl_add_u32 v8, v8, 1, v76
	s_waitcnt lgkmcnt(0)
	v_cvt_pk_bf16_f32 v72, v64, v65
	v_cvt_pk_bf16_f32 v73, v66, v67
	v_cvt_pk_bf16_f32 v74, v68, v69
	v_cvt_pk_bf16_f32 v75, v70, v71
	global_store_dwordx4 v8, v[72:75], s[40:41]
	s_add_u32 s32, s32, s54
	s_cmp_lt_u32 s32, s57
	s_cbranch_scc1 .Lw_item
.Lw_done:
	s_mov_b64 s[6:7], -1
